# p2a conv-stage and p4ret item-top waits no longer drain the previous item's global stores (counted waits adjusted; first-item path waits once)
# speedup vs baseline: 1.0038x; 1.0004x over previous
.LBB0_226:
	s_and_b32 s2, s64, 7
	s_lshl_b32 s65, s2, 7
	s_cmp_eq_u32 s2, s63
	v_add_u32_e32 v72, s65, v118
	s_cbranch_scc1 .LBB0_228
	v_mov_b32_e32 v73, v79
	v_readlane_b32 s72, v251, 8
	v_lshlrev_b64 v[32:33], 2, v[72:73]
	v_readlane_b32 s74, v251, 10
	v_readlane_b32 s75, v251, 11
	s_lshl_b32 s28, s65, 2
	v_readlane_b32 s73, v251, 9
	v_lshl_add_u64 v[34:35], s[74:75], 0, v[32:33]
	global_load_dword v93, v[34:35], off
	v_lshlrev_b64 v[34:35], 8, v[72:73]
	v_lshl_add_u64 v[36:37], v[88:89], 0, s[28:29]
	v_lshl_add_u64 v[48:49], v[80:81], 0, v[34:35]
	v_lshl_add_u64 v[52:53], v[82:83], 0, v[34:35]
	v_lshl_add_u64 v[96:97], s[16:17], 0, v[32:33]
	v_lshl_add_u64 v[98:99], s[72:73], 0, v[32:33]
	global_load_dwordx2 v[94:95], v[36:37], off
	global_load_dwordx4 v[40:43], v[48:49], off
	global_load_dwordx4 v[44:47], v[48:49], off offset:64
	global_load_dwordx4 v[32:35], v[52:53], off
	s_nop 0
	global_load_dwordx4 v[36:39], v[52:53], off offset:64
	global_load_dwordx4 v[56:59], v[48:49], off offset:128
	global_load_dwordx4 v[60:63], v[48:49], off offset:192
	s_nop 0
	global_load_dwordx4 v[48:51], v[52:53], off offset:128
	s_nop 0
	global_load_dwordx4 v[52:55], v[52:53], off offset:192
	s_nop 0
	global_load_dword v156, v[96:97], off
	global_load_dword v157, v[98:99], off
	v_lshl_add_u64 v[74:75], v[86:87], 0, s[28:29]
	v_add_co_u32_e32 v100, vcc, 0x1000, v74
	s_mov_b32 s63, s2
	s_nop 0
	v_addc_co_u32_e32 v101, vcc, 0, v75, vcc
	v_add_co_u32_e32 v96, vcc, 0x2000, v74
	v_readlane_b32 s76, v251, 12
	s_nop 0
	v_addc_co_u32_e32 v97, vcc, 0, v75, vcc
	v_add_co_u32_e32 v104, vcc, 0x3000, v74
	v_readlane_b32 s77, v251, 13
	s_nop 0
	v_addc_co_u32_e32 v105, vcc, 0, v75, vcc
	v_readlane_b32 s78, v251, 14
	v_readlane_b32 s79, v251, 15
	v_readlane_b32 s80, v251, 16
	v_readlane_b32 s81, v251, 17
	v_readlane_b32 s82, v251, 18
	v_readlane_b32 s83, v251, 19
	v_readlane_b32 s84, v251, 20
	v_readlane_b32 s85, v251, 21
	v_readlane_b32 s86, v251, 22
	v_readlane_b32 s87, v251, 23
	s_waitcnt vmcnt(11)
	v_mul_f32_e32 v73, 0xbfb8aa3b, v93
	v_fma_f32 v98, v93, s50, -v73
	v_rndne_f32_e32 v99, v73
	v_fmac_f32_e32 v98, 0xb2a5705f, v93
	v_sub_f32_e32 v73, v73, v99
	v_cvt_i32_f32_e32 v106, v99
	v_add_f32_e32 v73, v73, v98
	global_load_dwordx2 v[102:103], v[74:75], off
	s_nop 0
	global_load_dwordx2 v[100:101], v[100:101], off
	s_nop 0
	global_load_dwordx2 v[98:99], v[96:97], off
	s_nop 0
	global_load_dwordx2 v[96:97], v[104:105], off
	v_exp_f32_e32 v73, v73
	v_cmp_nlt_f32_e32 vcc, s51, v93
	v_ldexp_f32 v73, v73, v106
	s_nop 0
	v_cndmask_b32_e32 v73, 0, v73, vcc
	v_cmp_ngt_f32_e32 vcc, s52, v93
	s_nop 1
	v_cndmask_b32_e32 v73, v153, v73, vcc
	v_add_f32_e32 v93, 1.0, v73
	v_add_f32_e32 v104, -1.0, v93
	v_frexp_mant_f32_e32 v105, v93
	v_cvt_f64_f32_e32 v[74:75], v93
	v_sub_f32_e32 v106, v104, v93
	v_frexp_exp_i32_f64_e32 v74, v[74:75]
	v_cmp_gt_f32_e32 vcc, s54, v105
	v_sub_f32_e32 v104, v73, v104
	v_add_f32_e32 v75, 1.0, v106
	v_subbrev_co_u32_e32 v74, vcc, 0, v74, vcc
	v_add_f32_e32 v75, v104, v75
	v_sub_u32_e32 v104, 0, v74
	v_ldexp_f32 v93, v93, v104
	v_ldexp_f32 v75, v75, v104
	v_add_f32_e32 v104, -1.0, v93
	v_add_f32_e32 v106, 1.0, v93
	v_add_f32_e32 v105, 1.0, v104
	v_add_f32_e32 v107, -1.0, v106
	v_sub_f32_e32 v105, v93, v105
	v_sub_f32_e32 v93, v93, v107
	v_add_f32_e32 v107, v75, v105
	v_add_f32_e32 v75, v75, v93
	v_add_f32_e32 v93, v106, v75
	v_rcp_f32_e32 v160, v93
	v_add_f32_e32 v105, v104, v107
	v_sub_f32_e32 v106, v106, v93
	v_add_f32_e32 v75, v75, v106
	v_mul_f32_e32 v162, v105, v160
	v_mul_f32_e32 v106, v93, v162
	v_fma_f32 v158, v162, v93, -v106
	v_sub_f32_e32 v104, v104, v105
	v_fmac_f32_e32 v158, v162, v75
	v_add_f32_e32 v161, v107, v104
	v_add_f32_e32 v104, v106, v158
	v_sub_f32_e32 v107, v105, v104
	v_mov_b32_e32 v159, v104
	v_pk_add_f32 v[104:105], v[104:105], v[106:107] neg_lo:[0,1] neg_hi:[0,1]
	v_cvt_f32_i32_e32 v74, v74
	v_pk_add_f32 v[104:105], v[104:105], v[158:159] neg_lo:[0,1] neg_hi:[0,1]
	v_cmp_neq_f32_e32 vcc, s53, v73
	v_add_f32_e32 v105, v161, v105
	v_add_f32_e32 v104, v104, v105
	v_add_f32_e32 v105, v107, v104
	v_mul_f32_e32 v159, v160, v105
	v_mul_f32_e32 v106, v93, v159
	v_fma_f32 v158, v159, v93, -v106
	v_sub_f32_e32 v107, v107, v105
	v_fmac_f32_e32 v158, v159, v75
	v_add_f32_e32 v161, v104, v107
	v_add_f32_e32 v163, v162, v159
	v_add_f32_e32 v104, v106, v158
	v_sub_f32_e32 v93, v163, v162
	v_sub_f32_e32 v107, v105, v104
	v_sub_f32_e32 v75, v159, v93
	v_mov_b32_e32 v159, v104
	v_pk_add_f32 v[104:105], v[104:105], v[106:107] neg_lo:[0,1] neg_hi:[0,1]
	s_nop 0
	v_pk_add_f32 v[104:105], v[104:105], v[158:159] neg_lo:[0,1] neg_hi:[0,1]
	s_nop 0
	v_add_f32_e32 v93, v161, v105
	v_add_f32_e32 v93, v104, v93
	v_add_f32_e32 v93, v107, v93
	v_mul_f32_e32 v93, v160, v93
	v_add_f32_e32 v75, v75, v93
	v_add_f32_e32 v93, v163, v75
	v_mul_f32_e32 v104, v93, v93
	v_sub_f32_e32 v106, v93, v163
	v_fmamk_f32 v107, v104, 0x3e9b6dac, v147
	v_ldexp_f32 v105, v93, 1
	v_sub_f32_e32 v106, v75, v106
	v_mul_f32_e32 v75, v93, v104
	v_fmaak_f32 v93, v104, v107, 0x3f2aaada
	v_ldexp_f32 v159, v106, 1
	v_pk_mul_f32 v[106:107], v[74:75], v[92:93]
	s_nop 0
	v_fma_f32 v104, v74, s55, -v106
	v_fmac_f32_e32 v104, 0xb102e308, v74
	v_pk_add_f32 v[74:75], v[106:107], v[104:105]
	v_mov_b32_e32 v158, v106
	v_sub_f32_e32 v93, v75, v105
	v_sub_f32_e32 v93, v107, v93
	v_add_f32_e32 v159, v159, v93
	v_pk_add_f32 v[160:161], v[74:75], v[106:107] neg_lo:[0,1] neg_hi:[0,1]
	v_pk_add_f32 v[106:107], v[74:75], v[158:159]
	v_mov_b32_e32 v105, v74
	v_mov_b32_e32 v161, v107
	v_pk_add_f32 v[164:165], v[104:105], v[160:161] neg_lo:[0,1] neg_hi:[0,1]
	v_pk_add_f32 v[104:105], v[104:105], v[160:161]
	v_mov_b32_e32 v163, v74
	v_pk_add_f32 v[160:161], v[104:105], v[74:75] op_sel:[1,0] op_sel_hi:[0,1] neg_lo:[0,1] neg_hi:[0,1]
	v_mov_b32_e32 v162, v159
	v_mov_b32_e32 v158, v107
	v_mov_b32_e32 v159, v105
	v_pk_mov_b32 v[74:75], v[74:75], v[160:161] op_sel:[1,0]
	v_pk_add_f32 v[106:107], v[106:107], v[160:161] op_sel_hi:[1,0] neg_lo:[0,1] neg_hi:[0,1]
	v_pk_add_f32 v[74:75], v[158:159], v[74:75] neg_lo:[0,1] neg_hi:[0,1]
	v_mov_b32_e32 v106, v164
	v_pk_add_f32 v[74:75], v[162:163], v[74:75] neg_lo:[0,1] neg_hi:[0,1]
	v_mov_b32_e32 v165, v105
	v_pk_add_f32 v[106:107], v[106:107], v[74:75]
	s_nop 0
	v_pk_add_f32 v[158:159], v[106:107], v[106:107] op_sel:[0,1] op_sel_hi:[1,0]
	s_nop 0
	v_pk_add_f32 v[104:105], v[104:105], v[158:159] op_sel:[1,0] op_sel_hi:[0,1]
	v_mov_b32_e32 v107, v104
	v_pk_add_f32 v[160:161], v[106:107], v[164:165] neg_lo:[0,1] neg_hi:[0,1]
	v_mov_b32_e32 v75, v158
	v_sub_f32_e32 v93, v106, v160
	v_pk_add_f32 v[74:75], v[74:75], v[160:161] neg_lo:[0,1] neg_hi:[0,1]
	v_sub_f32_e32 v93, v164, v93
	v_add_f32_e32 v74, v74, v93
	v_add_f32_e32 v74, v74, v75
	v_add_f32_e32 v74, v104, v74
	v_cndmask_b32_e32 v74, v153, v74, vcc
	v_cmp_lt_f32_e64 vcc, |v73|, s56
	s_nop 1
	v_cndmask_b32_e32 v73, v74, v73, vcc
	v_mul_f32_e32 v93, 0xc1000000, v73
	s_waitcnt vmcnt(0)
.LBB0_228:
	s_waitcnt vmcnt(4)
	v_lshlrev_b32_e32 v74, 16, v109
	v_and_b32_e32 v75, 0xffff0000, v109
	v_lshlrev_b32_e32 v104, 16, v77
	v_and_b32_e32 v105, 0xffff0000, v77
	v_pk_fma_f32 v[74:75], v[102:103], v[74:75], v[94:95]
	v_lshlrev_b32_e32 v106, 16, v111
	v_and_b32_e32 v107, 0xffff0000, v111
	v_pk_fma_f32 v[74:75], v[100:101], v[104:105], v[74:75]
	v_pk_fma_f32 v[104:105], v[102:103], v[104:105], v[94:95]
	v_lshlrev_b32_e32 v158, 16, v110
	v_and_b32_e32 v159, 0xffff0000, v110
	v_pk_fma_f32 v[104:105], v[100:101], v[106:107], v[104:105]
	v_lshlrev_b32_e32 v160, 16, v113
	v_and_b32_e32 v161, 0xffff0000, v113
	v_pk_fma_f32 v[74:75], v[98:99], v[106:107], v[74:75]
	v_pk_fma_f32 v[104:105], v[98:99], v[158:159], v[104:105]
	v_pk_fma_f32 v[74:75], v[96:97], v[158:159], v[74:75]
	v_pk_fma_f32 v[104:105], v[96:97], v[160:161], v[104:105]
	ds_write2_b64 v148, v[74:75], v[104:105] offset1:66
	v_pk_fma_f32 v[74:75], v[102:103], v[106:107], v[94:95]
	v_pk_fma_f32 v[104:105], v[102:103], v[158:159], v[94:95]
	v_lshlrev_b32_e32 v162, 16, v112
	v_and_b32_e32 v163, 0xffff0000, v112
	v_pk_fma_f32 v[74:75], v[100:101], v[158:159], v[74:75]
	v_pk_fma_f32 v[104:105], v[100:101], v[160:161], v[104:105]
	v_lshlrev_b32_e32 v164, 16, v115
	v_and_b32_e32 v165, 0xffff0000, v115
	v_pk_fma_f32 v[74:75], v[98:99], v[160:161], v[74:75]
	v_pk_fma_f32 v[104:105], v[98:99], v[162:163], v[104:105]
	v_pk_fma_f32 v[74:75], v[96:97], v[162:163], v[74:75]
	v_pk_fma_f32 v[104:105], v[96:97], v[164:165], v[104:105]
	ds_write2_b64 v148, v[74:75], v[104:105] offset0:132 offset1:198
	v_pk_fma_f32 v[74:75], v[102:103], v[160:161], v[94:95]
	v_pk_fma_f32 v[104:105], v[102:103], v[162:163], v[94:95]
	v_lshlrev_b32_e32 v166, 16, v114
	v_and_b32_e32 v167, 0xffff0000, v114
	v_pk_fma_f32 v[74:75], v[100:101], v[162:163], v[74:75]
	v_pk_fma_f32 v[104:105], v[100:101], v[164:165], v[104:105]
	v_lshlrev_b32_e32 v168, 16, v119
	v_and_b32_e32 v169, 0xffff0000, v119
	v_pk_fma_f32 v[74:75], v[98:99], v[164:165], v[74:75]
	v_pk_fma_f32 v[104:105], v[98:99], v[166:167], v[104:105]
	v_pk_fma_f32 v[74:75], v[96:97], v[166:167], v[74:75]
	v_pk_fma_f32 v[104:105], v[96:97], v[168:169], v[104:105]
	v_add_u32_e32 v73, 0x800, v148
	ds_write2_b64 v73, v[74:75], v[104:105] offset0:8 offset1:74
	v_pk_fma_f32 v[74:75], v[102:103], v[164:165], v[94:95]
	v_pk_fma_f32 v[104:105], v[102:103], v[166:167], v[94:95]
	s_add_i32 s66, s64, s96
	v_lshlrev_b32_e32 v170, 16, v116
	v_and_b32_e32 v171, 0xffff0000, v116
	v_pk_fma_f32 v[74:75], v[100:101], v[166:167], v[74:75]
	v_pk_fma_f32 v[104:105], v[100:101], v[168:169], v[104:105]
	s_cmpk_gt_i32 s66, 0x3ff
	v_lshlrev_b32_e32 v172, 16, v120
	v_and_b32_e32 v173, 0xffff0000, v120
	v_pk_fma_f32 v[74:75], v[98:99], v[168:169], v[74:75]
	v_pk_fma_f32 v[104:105], v[98:99], v[170:171], v[104:105]
	s_cselect_b64 s[40:41], -1, 0
	v_pk_fma_f32 v[74:75], v[96:97], v[170:171], v[74:75]
	v_pk_fma_f32 v[104:105], v[96:97], v[172:173], v[104:105]
	s_and_b64 vcc, exec, s[40:41]
	ds_write2_b64 v73, v[74:75], v[104:105] offset0:140 offset1:206
	s_waitcnt lgkmcnt(0)
	s_barrier
	s_cbranch_vccnz .LBB0_230
	s_add_i32 s2, s47, s3
	s_and_b32 s6, s48, 0x380
	s_andn2_b32 s2, s2, 63
	s_lshl_b32 s28, s6, 1
	s_add_i32 s31, s2, s33
	v_lshl_add_u64 v[74:75], v[84:85], 0, s[28:29]
	v_mad_i64_i32 v[104:105], s[6:7], s31, v154, v[74:75]
	s_add_i32 s6, s31, 1
	s_nop 0
	v_mad_i64_i32 v[106:107], s[6:7], s6, v154, v[74:75]
	s_or_b32 s6, s31, 2
	s_add_i32 s2, s2, s19
	v_mad_i64_i32 v[110:111], s[6:7], s6, v154, v[74:75]
	v_mad_i64_i32 v[112:113], s[6:7], s2, v154, v[74:75]
	s_add_i32 s2, s31, 4
	v_mad_i64_i32 v[114:115], s[6:7], s2, v154, v[74:75]
	s_add_i32 s2, s31, 5
	v_mad_i64_i32 v[158:159], s[6:7], s2, v154, v[74:75]
	s_add_i32 s2, s31, 6
	v_mad_i64_i32 v[160:161], s[6:7], s2, v154, v[74:75]
	s_add_i32 s2, s31, 7
	v_mad_i64_i32 v[162:163], s[6:7], s2, v154, v[74:75]
	global_load_dword v109, v[104:105], off nt
	global_load_dword v77, v[106:107], off nt
	s_nop 0
	global_load_dword v111, v[110:111], off nt
	s_nop 0
	global_load_dword v110, v[112:113], off nt
	s_nop 0
	global_load_dword v113, v[114:115], off nt
	global_load_dword v112, v[158:159], off nt
	s_nop 0
	global_load_dword v115, v[160:161], off nt
	global_load_dword v114, v[162:163], off nt
	s_add_i32 s2, s31, 8
	v_mad_i64_i32 v[104:105], s[6:7], s2, v154, v[74:75]
	s_add_i32 s2, s31, 9
	s_add_i32 s31, s31, 10
	v_mad_i64_i32 v[106:107], s[6:7], s2, v154, v[74:75]
	v_mad_i64_i32 v[74:75], s[6:7], s31, v154, v[74:75]
	global_load_dword v119, v[104:105], off nt
	global_load_dword v116, v[106:107], off nt
	global_load_dword v120, v[74:75], off nt

.LBB0_394:
	s_and_b32 s41, s40, 7
	v_cvt_f32_ubyte0_e32 v64, s41
	v_sub_f32_e32 v64, 0xc0a00000, v64
	s_mov_b32 s2, 0xc2fc0000
	v_cmp_gt_f32_e32 vcc, s2, v64
	s_and_b64 s[16:17], vcc, exec
	s_cselect_b32 s2, 0xffffffc0, 0
	v_cndmask_b32_e32 v65, 0, v229, vcc
	v_add_f32_e32 v64, v64, v65
	v_exp_f32_e32 v64, v64
	s_and_b32 s42, s37, 0xffffff80
	v_add_u32_e32 v66, s42, v145
	v_cvt_f32_i32_e32 v92, v66
	v_ldexp_f32 v96, v64, s2
	v_sub_f32_e32 v97, 1.0, v96
	v_frexp_mant_f32_e32 v64, v97
	s_mov_b32 s2, 0x3f2aaaab
	v_cmp_gt_f32_e64 s[68:69], s2, v64
	s_add_i32 s2, s33, 0
	v_lshl_add_u64 v[64:65], v[134:135], 0, v[132:133]
	s_add_i32 m0, s2, 0x19800
	v_mul_f32_e32 v66, v148, v92
	global_load_lds_dwordx4 v[64:65], off
	v_lshl_add_u64 v[64:65], v[134:135], 0, v[136:137]
	s_add_i32 m0, s2, 0x1b800
	v_fract_f32_e32 v67, v66
	global_load_lds_dwordx4 v[64:65], off
	v_lshl_add_u64 v[64:65], v[134:135], 0, v[138:139]
	s_add_i32 m0, s2, 0x1d800
	v_fma_f32 v66, v92, v148, -v66
	global_load_lds_dwordx4 v[64:65], off
	v_lshl_add_u64 v[64:65], v[134:135], 0, v[140:141]
	s_add_i32 m0, s2, 0x1f800
	v_mul_f32_e32 v68, v150, v92
	global_load_lds_dwordx4 v[64:65], off
	v_mul_f32_e32 v64, v146, v92
	v_fract_f32_e32 v65, v64
	v_fma_f32 v64, v92, v146, -v64
	v_fmac_f32_e32 v64, v147, v92
	v_add_f32_e32 v64, v65, v64
	v_fmac_f32_e32 v66, v149, v92
	v_fract_f32_e32 v69, v68
	v_fma_f32 v68, v92, v150, -v68
	v_mul_f32_e32 v70, v152, v92
	v_sin_f32_e32 v65, v64
	v_cos_f32_e32 v64, v64
	v_add_f32_e32 v66, v67, v66
	v_fmac_f32_e32 v68, v151, v92
	v_fract_f32_e32 v71, v70
	v_fma_f32 v70, v92, v152, -v70
	v_mul_f32_e32 v72, v154, v92
	v_sin_f32_e32 v67, v66
	v_cos_f32_e32 v66, v66
	v_add_f32_e32 v68, v69, v68
	v_fmac_f32_e32 v70, v153, v92
	v_fract_f32_e32 v73, v72
	v_fma_f32 v72, v92, v154, -v72
	v_mul_f32_e32 v74, v156, v92
	v_sin_f32_e32 v69, v68
	v_cos_f32_e32 v68, v68
	v_add_f32_e32 v70, v71, v70
	v_fmac_f32_e32 v72, v155, v92
	v_fract_f32_e32 v75, v74
	v_fma_f32 v74, v92, v156, -v74
	v_mul_f32_e32 v76, v158, v92
	v_sin_f32_e32 v71, v70
	v_add_f32_e32 v72, v73, v72
	v_fmac_f32_e32 v74, v157, v92
	v_fract_f32_e32 v77, v76
	v_fma_f32 v76, v92, v158, -v76
	v_mul_f32_e32 v78, v160, v92
	s_waitcnt vmcnt(8)
	v_lshlrev_b32_e32 v82, 16, v16
	v_cos_f32_e32 v70, v70
	v_sin_f32_e32 v73, v72
	v_add_f32_e32 v74, v75, v74
	v_fmac_f32_e32 v76, v159, v92
	v_fract_f32_e32 v79, v78
	v_fma_f32 v78, v92, v160, -v78
	v_lshlrev_b32_e32 v80, 16, v40
	v_and_b32_e32 v83, 0xffff0000, v16
	v_mul_f32_e32 v99, v65, v82
	v_mul_f32_e32 v82, v64, v82
	v_cos_f32_e32 v72, v72
	v_sin_f32_e32 v75, v74
	v_add_f32_e32 v76, v77, v76
	v_fmac_f32_e32 v78, v161, v92
	v_and_b32_e32 v81, 0xffff0000, v40
	v_lshlrev_b32_e32 v86, 16, v17
	v_fma_f32 v99, v64, v80, -v99
	v_fmac_f32_e32 v82, v65, v80
	v_mul_f32_e32 v80, v67, v83
	v_mul_f32_e32 v83, v66, v83
	v_cos_f32_e32 v74, v74
	v_sin_f32_e32 v77, v76
	v_add_f32_e32 v78, v79, v78
	v_lshlrev_b32_e32 v84, 16, v41
	v_and_b32_e32 v87, 0xffff0000, v17
	v_fma_f32 v80, v66, v81, -v80
	v_fmac_f32_e32 v83, v67, v81
	v_mul_f32_e32 v81, v69, v86
	v_mul_f32_e32 v86, v68, v86
	v_cos_f32_e32 v76, v76
	v_sin_f32_e32 v79, v78
	v_and_b32_e32 v85, 0xffff0000, v41
	v_lshlrev_b32_e32 v90, 16, v18
	v_fma_f32 v81, v68, v84, -v81
	v_fmac_f32_e32 v86, v69, v84
	v_mul_f32_e32 v84, v71, v87
	v_cos_f32_e32 v78, v78
	v_lshlrev_b32_e32 v88, 16, v42
	v_and_b32_e32 v91, 0xffff0000, v18
	v_fma_f32 v100, v70, v85, -v84
	v_mul_f32_e32 v84, v73, v90
	v_and_b32_e32 v89, 0xffff0000, v42
	v_lshlrev_b32_e32 v95, 16, v19
	v_fma_f32 v101, v72, v88, -v84
	v_mul_f32_e32 v90, v72, v90
	v_mul_f32_e32 v84, v75, v91
	v_lshlrev_b32_e32 v93, 16, v43
	v_and_b32_e32 v98, 0xffff0000, v19
	v_mul_f32_e32 v87, v70, v87
	v_fmac_f32_e32 v90, v73, v88
	v_fma_f32 v88, v74, v89, -v84
	v_mul_f32_e32 v91, v74, v91
	v_mul_f32_e32 v84, v77, v95
	v_and_b32_e32 v94, 0xffff0000, v43
	v_fmac_f32_e32 v87, v71, v85
	v_fmac_f32_e32 v91, v75, v89
	v_fma_f32 v89, v76, v93, -v84
	v_mul_f32_e32 v95, v76, v95
	v_mul_f32_e32 v84, v79, v98
	v_fmac_f32_e32 v95, v77, v93
	v_fma_f32 v93, v78, v94, -v84
	v_cvt_pk_bf16_f32 v84, v99, v80
	v_cvt_pk_bf16_f32 v80, v82, v83
	v_cvt_pk_bf16_f32 v85, v81, v100
	v_cvt_pk_bf16_f32 v81, v86, v87
	v_cvt_pk_bf16_f32 v86, v101, v88
	v_cvt_pk_bf16_f32 v82, v90, v91
	v_cvt_pk_bf16_f32 v87, v89, v93
	v_lshlrev_b32_e32 v89, 16, v32
	v_lshlrev_b32_e32 v88, 16, v36
	v_pk_mul_f32 v[90:91], v[64:65], v[88:89]
	v_mul_f32_e32 v98, v78, v98
	v_sub_f32_e32 v90, v90, v91
	v_mul_f32_e32 v93, 0x3db504f3, v90
	v_mov_b32_e32 v90, v65
	v_mov_b32_e32 v91, v64
	v_pk_mul_f32 v[64:65], v[90:91], v[88:89]
	v_fmac_f32_e32 v98, v79, v94
	v_add_f32_e32 v64, v64, v65
	v_mul_f32_e32 v90, 0x3db504f3, v64
	v_and_b32_e32 v65, 0xffff0000, v32
	v_and_b32_e32 v64, 0xffff0000, v36
	v_pk_mul_f32 v[88:89], v[66:67], v[64:65]
	v_cvt_pk_bf16_f32 v83, v95, v98
	v_and_b32_e32 v95, 0xffff0000, v25
	v_sub_f32_e32 v88, v88, v89
	v_mul_f32_e32 v91, 0x3db504f3, v88
	v_mov_b32_e32 v88, v67
	v_mov_b32_e32 v89, v66
	v_pk_mul_f32 v[64:65], v[88:89], v[64:65]
	v_lshlrev_b32_e32 v108, 16, v26
	v_add_f32_e32 v64, v64, v65
	v_mul_f32_e32 v88, 0x3db504f3, v64
	v_lshlrev_b32_e32 v65, 16, v33
	v_lshlrev_b32_e32 v64, 16, v37
	v_pk_mul_f32 v[66:67], v[68:69], v[64:65]
	v_lshlrev_b32_e32 v106, 16, v14
	v_sub_f32_e32 v66, v66, v67
	v_mul_f32_e32 v89, 0x3db504f3, v66
	v_mov_b32_e32 v66, v69
	v_mov_b32_e32 v67, v68
	v_pk_mul_f32 v[64:65], v[66:67], v[64:65]
	v_cvt_pk_bf16_f32 v68, v93, v91
	v_and_b32_e32 v91, 0xffff0000, v24
	v_add_f32_e32 v64, v64, v65
	v_mul_f32_e32 v94, 0x3db504f3, v64
	v_and_b32_e32 v65, 0xffff0000, v33
	v_and_b32_e32 v64, 0xffff0000, v37
	v_pk_mul_f32 v[66:67], v[70:71], v[64:65]
	v_and_b32_e32 v93, 0xffff0000, v13
	v_sub_f32_e32 v66, v66, v67
	v_mul_f32_e32 v69, 0x3db504f3, v66
	v_mov_b32_e32 v66, v71
	v_mov_b32_e32 v67, v70
	v_pk_mul_f32 v[64:65], v[66:67], v[64:65]
	v_and_b32_e32 v109, 0xffff0000, v26
	v_add_f32_e32 v64, v64, v65
	v_mul_f32_e32 v70, 0x3db504f3, v64
	v_lshlrev_b32_e32 v65, 16, v34
	v_lshlrev_b32_e32 v64, 16, v38
	v_pk_mul_f32 v[66:67], v[72:73], v[64:65]
	v_and_b32_e32 v107, 0xffff0000, v14
	v_sub_f32_e32 v66, v66, v67
	v_mul_f32_e32 v71, 0x3db504f3, v66
	v_mov_b32_e32 v66, v73
	v_mov_b32_e32 v67, v72
	v_pk_mul_f32 v[64:65], v[66:67], v[64:65]
	v_lshlrev_b32_e32 v112, 16, v27
	v_add_f32_e32 v64, v64, v65
	v_mul_f32_e32 v72, 0x3db504f3, v64
	v_and_b32_e32 v65, 0xffff0000, v34
	v_and_b32_e32 v64, 0xffff0000, v38
	v_pk_mul_f32 v[66:67], v[74:75], v[64:65]
	v_lshlrev_b32_e32 v110, 16, v15
	v_sub_f32_e32 v66, v66, v67
	v_mul_f32_e32 v73, 0x3db504f3, v66
	v_mov_b32_e32 v66, v75
	v_mov_b32_e32 v67, v74
	v_pk_mul_f32 v[64:65], v[66:67], v[64:65]
	v_and_b32_e32 v113, 0xffff0000, v27
	v_add_f32_e32 v64, v64, v65
	v_mul_f32_e32 v74, 0x3db504f3, v64
	v_lshlrev_b32_e32 v65, 16, v35
	v_lshlrev_b32_e32 v64, 16, v39
	v_pk_mul_f32 v[66:67], v[76:77], v[64:65]
	v_and_b32_e32 v111, 0xffff0000, v15
	v_sub_f32_e32 v66, v66, v67
	v_mul_f32_e32 v75, 0x3db504f3, v66
	v_mov_b32_e32 v66, v77
	v_mov_b32_e32 v67, v76
	v_pk_mul_f32 v[64:65], v[66:67], v[64:65]
	s_add_i32 s40, s40, s44
	v_add_f32_e32 v64, v64, v65
	v_mul_f32_e32 v76, 0x3db504f3, v64
	v_and_b32_e32 v65, 0xffff0000, v35
	v_and_b32_e32 v64, 0xffff0000, v39
	v_pk_mul_f32 v[66:67], v[78:79], v[64:65]
	s_cmpk_gt_i32 s40, 0x1ff
	v_sub_f32_e32 v66, v66, v67
	v_mul_f32_e32 v77, 0x3db504f3, v66
	v_mov_b32_e32 v66, v79
	v_mov_b32_e32 v67, v78
	v_pk_mul_f32 v[64:65], v[66:67], v[64:65]
	v_mul_f32_e32 v78, v168, v92
	v_add_f32_e32 v64, v64, v65
	v_mul_f32_e32 v67, 0x3db504f3, v64
	v_cvt_pk_bf16_f32 v64, v90, v88
	v_mul_f32_e32 v88, v170, v92
	v_cvt_pk_bf16_f32 v69, v89, v69
	v_fract_f32_e32 v89, v88
	v_fma_f32 v88, v92, v170, -v88
	v_fmac_f32_e32 v88, v171, v92
	v_add_f32_e32 v88, v89, v88
	v_sin_f32_e32 v99, v88
	v_cos_f32_e32 v98, v88
	v_mul_f32_e32 v88, v172, v92
	v_fract_f32_e32 v89, v88
	v_fma_f32 v88, v92, v172, -v88
	v_fmac_f32_e32 v88, v173, v92
	v_add_f32_e32 v88, v89, v88
	v_cvt_pk_bf16_f32 v65, v94, v70
	v_cvt_pk_bf16_f32 v70, v71, v73
	v_cvt_pk_bf16_f32 v66, v72, v74
	v_mul_f32_e32 v72, v162, v92
	v_sin_f32_e32 v101, v88
	v_cos_f32_e32 v100, v88
	v_mul_f32_e32 v88, v174, v92
	v_fract_f32_e32 v73, v72
	v_fma_f32 v72, v92, v162, -v72
	v_mul_f32_e32 v74, v164, v92
	v_fract_f32_e32 v89, v88
	v_fma_f32 v88, v92, v174, -v88
	v_cvt_pk_bf16_f32 v71, v75, v77
	v_cvt_pk_bf16_f32 v67, v76, v67
	v_fmac_f32_e32 v72, v163, v92
	v_fract_f32_e32 v75, v74
	v_fma_f32 v74, v92, v164, -v74
	v_mul_f32_e32 v76, v166, v92
	v_fmac_f32_e32 v88, v175, v92
	v_add_f32_e32 v72, v73, v72
	v_fmac_f32_e32 v74, v165, v92
	v_fract_f32_e32 v77, v76
	v_fma_f32 v76, v92, v166, -v76
	v_add_f32_e32 v88, v89, v88
	v_sin_f32_e32 v73, v72
	v_cos_f32_e32 v72, v72
	v_add_f32_e32 v74, v75, v74
	v_fmac_f32_e32 v76, v167, v92
	v_fract_f32_e32 v79, v78
	v_fma_f32 v78, v92, v168, -v78
	v_sin_f32_e32 v103, v88
	v_cos_f32_e32 v102, v88
	v_mul_f32_e32 v88, v176, v92
	v_sin_f32_e32 v75, v74
	v_cos_f32_e32 v74, v74
	v_add_f32_e32 v76, v77, v76
	v_fmac_f32_e32 v78, v169, v92
	v_fract_f32_e32 v89, v88
	v_fma_f32 v88, v92, v176, -v88
	v_sin_f32_e32 v77, v76
	v_cos_f32_e32 v76, v76
	v_add_f32_e32 v78, v79, v78
	v_fmac_f32_e32 v88, v177, v92
	v_sin_f32_e32 v79, v78
	v_add_f32_e32 v88, v89, v88
	v_lshlrev_b32_e32 v90, 16, v24
	v_cos_f32_e32 v78, v78
	v_sin_f32_e32 v105, v88
	v_cos_f32_e32 v104, v88
	v_lshlrev_b32_e32 v88, 16, v12
	v_mul_f32_e32 v114, v73, v90
	v_mul_f32_e32 v90, v72, v90
	v_and_b32_e32 v89, 0xffff0000, v12
	v_lshlrev_b32_e32 v94, 16, v25
	v_fma_f32 v114, v72, v88, -v114
	v_fmac_f32_e32 v90, v73, v88
	v_mul_f32_e32 v88, v75, v91
	v_mul_f32_e32 v91, v74, v91
	v_lshlrev_b32_e32 v92, 16, v13
	v_fma_f32 v88, v74, v89, -v88
	v_fmac_f32_e32 v91, v75, v89
	v_mul_f32_e32 v89, v77, v94
	v_mul_f32_e32 v94, v76, v94
	v_fma_f32 v89, v76, v92, -v89
	v_fmac_f32_e32 v94, v77, v92
	v_mul_f32_e32 v92, v79, v95
	v_fma_f32 v115, v78, v93, -v92
	v_mul_f32_e32 v92, v99, v108
	v_fma_f32 v116, v98, v106, -v92
	v_mul_f32_e32 v108, v98, v108
	v_mul_f32_e32 v92, v101, v109
	v_mul_f32_e32 v95, v78, v95
	v_fmac_f32_e32 v108, v99, v106
	v_fma_f32 v106, v100, v107, -v92
	v_mul_f32_e32 v109, v100, v109
	v_mul_f32_e32 v92, v103, v112
	v_fmac_f32_e32 v95, v79, v93
	v_fmac_f32_e32 v109, v101, v107
	v_fma_f32 v107, v102, v110, -v92
	v_mul_f32_e32 v112, v102, v112
	v_mul_f32_e32 v92, v105, v113
	v_fmac_f32_e32 v112, v103, v110
	v_fma_f32 v110, v104, v111, -v92
	v_cvt_pk_bf16_f32 v92, v114, v88
	v_cvt_pk_bf16_f32 v88, v90, v91
	v_cvt_pk_bf16_f32 v93, v89, v115
	v_cvt_pk_bf16_f32 v89, v94, v95
	v_cvt_pk_bf16_f32 v94, v116, v106
	v_cvt_pk_bf16_f32 v90, v108, v109
	v_cvt_pk_bf16_f32 v95, v107, v110
	v_lshlrev_b32_e32 v107, 16, v44
	v_lshlrev_b32_e32 v106, 16, v28
	v_pk_mul_f32 v[108:109], v[72:73], v[106:107]
	v_mul_f32_e32 v113, v104, v113
	v_sub_f32_e32 v108, v108, v109
	v_mul_f32_e32 v110, 0x3db504f3, v108
	v_mov_b32_e32 v108, v73
	v_mov_b32_e32 v109, v72
	v_pk_mul_f32 v[72:73], v[108:109], v[106:107]
	v_fmac_f32_e32 v113, v105, v111
	v_add_f32_e32 v72, v72, v73
	v_mul_f32_e32 v108, 0x3db504f3, v72
	v_and_b32_e32 v73, 0xffff0000, v44
	v_and_b32_e32 v72, 0xffff0000, v28
	v_pk_mul_f32 v[106:107], v[74:75], v[72:73]
	v_cvt_pk_bf16_f32 v91, v112, v113
	s_cselect_b64 s[34:35], -1, 0
	v_sub_f32_e32 v106, v106, v107
	v_mul_f32_e32 v109, 0x3db504f3, v106
	v_mov_b32_e32 v106, v75
	v_mov_b32_e32 v107, v74
	v_pk_mul_f32 v[72:73], v[106:107], v[72:73]
	s_and_b64 vcc, exec, s[34:35]
	v_add_f32_e32 v72, v72, v73
	v_mul_f32_e32 v106, 0x3db504f3, v72
	v_lshlrev_b32_e32 v73, 16, v45
	v_lshlrev_b32_e32 v72, 16, v29
	v_pk_mul_f32 v[74:75], v[76:77], v[72:73]
	s_nop 0
	v_sub_f32_e32 v74, v74, v75
	v_mul_f32_e32 v107, 0x3db504f3, v74
	v_mov_b32_e32 v74, v77
	v_mov_b32_e32 v75, v76
	v_pk_mul_f32 v[72:73], v[74:75], v[72:73]
	s_nop 0
	v_add_f32_e32 v72, v72, v73
	v_mul_f32_e32 v77, 0x3db504f3, v72
	v_and_b32_e32 v73, 0xffff0000, v45
	v_and_b32_e32 v72, 0xffff0000, v29
	v_pk_mul_f32 v[74:75], v[78:79], v[72:73]
	s_nop 0
	v_sub_f32_e32 v74, v74, v75
	v_mul_f32_e32 v111, 0x3db504f3, v74
	v_mov_b32_e32 v74, v79
	v_mov_b32_e32 v75, v78
	v_pk_mul_f32 v[72:73], v[74:75], v[72:73]
	s_nop 0
	v_add_f32_e32 v72, v72, v73
	v_mul_f32_e32 v78, 0x3db504f3, v72
	v_lshlrev_b32_e32 v73, 16, v46
	v_lshlrev_b32_e32 v72, 16, v30
	v_pk_mul_f32 v[74:75], v[98:99], v[72:73]
	s_nop 0
	v_sub_f32_e32 v74, v74, v75
	v_mul_f32_e32 v79, 0x3db504f3, v74
	v_mov_b32_e32 v74, v99
	v_mov_b32_e32 v75, v98
	v_pk_mul_f32 v[72:73], v[74:75], v[72:73]
	s_nop 0
	v_add_f32_e32 v72, v72, v73
	v_mul_f32_e32 v98, 0x3db504f3, v72
	v_and_b32_e32 v73, 0xffff0000, v46
	v_and_b32_e32 v72, 0xffff0000, v30
	v_pk_mul_f32 v[74:75], v[100:101], v[72:73]
	s_nop 0
	v_sub_f32_e32 v74, v74, v75
	v_mul_f32_e32 v99, 0x3db504f3, v74
	v_mov_b32_e32 v74, v101
	v_mov_b32_e32 v75, v100
	v_pk_mul_f32 v[72:73], v[74:75], v[72:73]
	s_nop 0
	v_add_f32_e32 v72, v72, v73
	v_mul_f32_e32 v100, 0x3db504f3, v72
	v_lshlrev_b32_e32 v73, 16, v47
	v_lshlrev_b32_e32 v72, 16, v31
	v_pk_mul_f32 v[74:75], v[102:103], v[72:73]
	s_nop 0
	v_sub_f32_e32 v74, v74, v75
	v_mul_f32_e32 v101, 0x3db504f3, v74
	v_mov_b32_e32 v74, v103
	v_mov_b32_e32 v75, v102
	v_pk_mul_f32 v[72:73], v[74:75], v[72:73]
	s_nop 0
	v_add_f32_e32 v72, v72, v73
	v_mul_f32_e32 v102, 0x3db504f3, v72
	v_and_b32_e32 v73, 0xffff0000, v47
	v_and_b32_e32 v72, 0xffff0000, v31
	v_pk_mul_f32 v[74:75], v[104:105], v[72:73]
	s_nop 0
	v_sub_f32_e32 v74, v74, v75
	v_mul_f32_e32 v103, 0x3db504f3, v74
	v_mov_b32_e32 v74, v105
	v_mov_b32_e32 v75, v104
	v_pk_mul_f32 v[72:73], v[74:75], v[72:73]
	s_nop 0
	v_add_f32_e32 v72, v72, v73
	v_mul_f32_e32 v104, 0x3db504f3, v72
	v_cvt_pk_bf16_f32 v72, v110, v109
	v_cvt_pk_bf16_f32 v76, v108, v106
	v_cvt_pk_bf16_f32 v73, v107, v111
	v_cvt_pk_bf16_f32 v77, v77, v78
	v_cvt_pk_bf16_f32 v74, v79, v99
	v_cvt_pk_bf16_f32 v78, v98, v100
	v_cvt_pk_bf16_f32 v75, v101, v103
	v_cvt_pk_bf16_f32 v79, v102, v104
	ds_write_b128 v222, v[68:71]
	ds_write_b16 v182, v0 offset:34816
	ds_write_b16_d16_hi v182, v0 offset:35088
	ds_write_b16 v182, v1 offset:35360
	ds_write_b16_d16_hi v182, v1 offset:35632
	ds_write_b16 v182, v2 offset:35904
	ds_write_b16_d16_hi v182, v2 offset:36176
	ds_write_b16 v182, v3 offset:36448
	ds_write_b16_d16_hi v182, v3 offset:36720
	ds_write_b128 v222, v[72:75] offset:64
	ds_write_b16 v183, v4 offset:34816
	ds_write_b16_d16_hi v183, v4 offset:35088
	ds_write_b16 v182, v5 offset:44064
	ds_write_b16_d16_hi v182, v5 offset:44336
	ds_write_b16 v182, v6 offset:44608
	ds_write_b16_d16_hi v182, v6 offset:44880
	ds_write_b16 v182, v7 offset:45152
	ds_write_b16_d16_hi v182, v7 offset:45424
	ds_write_b128 v222, v[64:67] offset:128
	ds_write_b16 v182, v20 offset:52224
	ds_write_b16_d16_hi v182, v20 offset:52496
	ds_write_b16 v182, v21 offset:52768
	ds_write_b16_d16_hi v182, v21 offset:53040
	ds_write_b16 v182, v22 offset:53312
	ds_write_b16_d16_hi v182, v22 offset:53584
	ds_write_b16 v182, v23 offset:53856
	ds_write_b16_d16_hi v182, v23 offset:54128
	ds_write_b128 v222, v[76:79] offset:192
	ds_write_b16 v182, v8 offset:60928
	ds_write_b16_d16_hi v182, v8 offset:61200
	ds_write_b16 v182, v9 offset:61472
	ds_write_b16_d16_hi v182, v9 offset:61744
	ds_write_b16 v182, v10 offset:62016
	ds_write_b16_d16_hi v182, v10 offset:62288
	ds_write_b16 v182, v11 offset:62560
	ds_write_b16_d16_hi v182, v11 offset:62832
	s_waitcnt vmcnt(0)
	v_mov_b32_e32 v72, v60
	v_mov_b32_e32 v73, v61
	v_mov_b32_e32 v74, v62
	v_mov_b32_e32 v75, v63
	v_mov_b32_e32 v64, v56
	v_mov_b32_e32 v65, v57
	v_mov_b32_e32 v66, v58
	v_mov_b32_e32 v67, v59
	v_mov_b32_e32 v68, v52
	v_mov_b32_e32 v69, v53
	v_mov_b32_e32 v70, v54
	v_mov_b32_e32 v71, v55
	v_mov_b32_e32 v76, v48
	v_mov_b32_e32 v77, v49
	v_mov_b32_e32 v78, v50
	v_mov_b32_e32 v79, v51
	s_waitcnt lgkmcnt(0)
	s_barrier
	s_cbranch_vccnz .LBB0_396
	s_add_i32 s2, s36, s37
	v_readlane_b32 s16, v251, 37
	s_and_b32 s2, s2, 0xffffff80
	v_readlane_b32 s17, v251, 38
	v_add_u32_e32 v0, s2, v145
	v_mov_b32_e32 v143, v131
	v_mov_b64_e32 v[64:65], s[16:17]
	v_mad_i64_i32 v[0:1], s[16:17], v0, s97, v[64:65]
	s_and_b32 s16, s38, 0x380
	s_lshl_b32 s46, s16, 1
	v_lshl_add_u64 v[0:1], v[0:1], 0, s[46:47]
	v_lshl_add_u64 v[0:1], v[0:1], 0, v[142:143]
	v_add_co_u32_e32 v8, vcc, 0x1000, v0
	v_add_u32_e32 v66, s2, v179
	s_nop 0
	v_addc_co_u32_e32 v9, vcc, 0, v1, vcc
	v_add_co_u32_e32 v10, vcc, s3, v0
	v_mad_i64_i32 v[64:65], s[16:17], v66, s97, v[64:65]
	s_nop 0
	v_addc_co_u32_e32 v11, vcc, 0, v1, vcc
	global_load_dwordx4 v[40:43], v[8:9], off nt
	global_load_dwordx4 v[12:15], v[8:9], off offset:64 nt
	global_load_dwordx4 v[36:39], v[8:9], off offset:2048 nt
	global_load_dwordx4 v[28:31], v[8:9], off offset:2112 nt
	global_load_dwordx4 v[0:3], v[10:11], off nt
	global_load_dwordx4 v[4:7], v[10:11], off offset:64 nt
	global_load_dwordx4 v[16:19], v[8:9], off offset:128 nt
	global_load_dwordx4 v[24:27], v[8:9], off offset:192 nt
	global_load_dwordx4 v[32:35], v[8:9], off offset:2176 nt
	global_load_dwordx4 v[44:47], v[8:9], off offset:2240 nt
	global_load_dwordx4 v[20:23], v[10:11], off offset:128 nt
	s_nop 0
	global_load_dwordx4 v[8:11], v[10:11], off offset:192 nt
	v_lshl_add_u64 v[64:65], v[64:65], 0, s[46:47]
	v_lshl_add_u64 v[64:65], v[64:65], 0, v[130:131]
	s_mov_b64 s[16:17], 0x2800
	v_add_co_u32_e32 v72, vcc, s3, v64
	v_lshl_add_u64 v[76:77], v[64:65], 0, s[16:17]
	s_nop 0
	v_addc_co_u32_e32 v73, vcc, 0, v65, vcc
	global_load_dwordx4 v[64:67], v[76:77], off offset:16 nt
	global_load_dwordx4 v[68:71], v[76:77], off offset:32 nt
	s_nop 0
	global_load_dwordx4 v[72:75], v[72:73], off offset:2048 nt
	s_nop 0
	global_load_dwordx4 v[76:79], v[76:77], off offset:48 nt
